# v14 plus work-balance remaps plus batched prep_unit V-tile staging loads
# baseline (speedup 1.0000x reference)
.LBB0_687:
	s_barrier
	s_and_saveexec_b64 s[14:15], s[6:7]
	s_cbranch_execz .LBB0_686
	s_and_b64 s[18:19], s[16:17], exec
	s_cselect_b32 s10, s30, 0xa40
	s_add_u32 s18, s0, s10
	s_addc_u32 s19, s1, 0
	v_ashrrev_i32_e32 v11, 5, v64
	v_mov_b64_e32 v[12:13], s[18:19]
	v_lshlrev_b32_e32 v14, 1, v8
	v_add_u32_e32 v15, s2, v11
	v_and_b32_e32 v18, 0x1f0, v14
	v_mad_i64_i32 v[12:13], s[38:39], v15, s3, v[12:13]
	v_lshl_add_u64 v[36:37], v[12:13], 0, v[18:19]
	s_mov_b32 s23, 0
	s_mov_b32 s22, 0x16400
	v_lshl_add_u64 v[38:39], v[36:37], 0, s[22:23]
	v_lshl_add_u64 v[40:41], v[38:39], 0, s[22:23]
	v_lshl_add_u64 v[42:43], v[40:41], 0, s[22:23]
	global_load_dwordx4 v[12:15], v[36:37], off
	global_load_dwordx4 v[24:27], v[38:39], off
	global_load_dwordx4 v[28:31], v[40:41], off
	global_load_dwordx4 v[32:35], v[42:43], off
	v_mul_lo_u32 v11, v11, s31
	v_add3_u32 v11, 0, v11, v18
	s_waitcnt vmcnt(3)
	ds_write_b128 v11, v[12:15] offset:256
	s_waitcnt vmcnt(2)
	ds_write_b128 v11, v[24:27] offset:8704
	s_waitcnt vmcnt(1)
	ds_write_b128 v11, v[28:31] offset:17152
	s_waitcnt vmcnt(0)
	ds_write_b128 v11, v[32:35] offset:25600
	s_branch .LBB0_686
